# MoBA gating: waves whose 8 candidate blocks are all masked (>= own block) skip the score loop
# speedup vs baseline: 1.0111x; 1.0016x over previous
.LBB0_93:
	s_xor_b64 s[56:57], s[0:1], -1
	s_and_b64 s[0:1], s[0:1], exec
	s_cselect_b32 s8, s43, s44
	s_lshl_b32 s46, s8, 7
	s_ashr_i32 s1, s46, 31
	s_add_u32 s0, s46, s6
	s_addc_u32 s1, s1, 0
	v_lshl_add_u64 v[36:37], s[0:1], 0, v[116:117]
	v_mov_b64_e32 v[40:41], s[88:89]
	v_mad_u64_u32 v[38:39], s[10:11], v36, s72, v[40:41]
	v_mad_i32_i24 v39, v37, s72, v39
	s_lshl_b32 s20, s45, 1
	v_lshl_add_u64 v[36:37], v[38:39], 0, s[20:21]
	v_lshl_add_u64 v[36:37], v[36:37], 0, v[2:3]
	v_add_co_u32_e32 v36, vcc, s3, v36
	s_nop 1
	v_addc_co_u32_e32 v37, vcc, 0, v37, vcc
	global_load_dwordx4 v[4:7], v[36:37], off
	v_lshl_add_u64 v[36:37], s[0:1], 0, v[122:123]
	v_mad_u64_u32 v[38:39], s[10:11], v36, s72, v[40:41]
	v_mad_i32_i24 v39, v37, s72, v39
	v_lshl_add_u64 v[36:37], v[38:39], 0, s[20:21]
	v_lshl_add_u64 v[36:37], v[36:37], 0, v[2:3]
	v_add_co_u32_e32 v36, vcc, s3, v36
	s_nop 1
	v_addc_co_u32_e32 v37, vcc, 0, v37, vcc
	global_load_dwordx4 v[8:11], v[36:37], off
	v_lshl_add_u64 v[36:37], s[0:1], 0, v[124:125]
	v_mad_u64_u32 v[38:39], s[10:11], v36, s72, v[40:41]
	v_mad_i32_i24 v39, v37, s72, v39
	v_lshl_add_u64 v[36:37], v[38:39], 0, s[20:21]
	v_lshl_add_u64 v[36:37], v[36:37], 0, v[2:3]
	v_add_co_u32_e32 v36, vcc, s3, v36
	s_nop 1
	v_addc_co_u32_e32 v37, vcc, 0, v37, vcc
	global_load_dwordx4 v[12:15], v[36:37], off
	v_lshl_add_u64 v[36:37], s[0:1], 0, v[126:127]
	v_mad_u64_u32 v[38:39], s[0:1], v36, s72, v[40:41]
	v_mad_i32_i24 v39, v37, s72, v39
	v_lshl_add_u64 v[36:37], v[38:39], 0, s[20:21]
	v_lshl_add_u64 v[36:37], v[36:37], 0, v[2:3]
	v_add_co_u32_e32 v36, vcc, 0x1000, v36
	s_nop 1
	v_addc_co_u32_e32 v37, vcc, 0, v37, vcc
	global_load_dwordx4 v[16:19], v[36:37], off
	v_lshrrev_b32_e32 v36, 5, v173
	v_lshlrev_b32_e32 v36, 9, v36
	v_mov_b32_e32 v37, 0
	v_lshl_add_u64 v[36:37], v[142:143], 0, v[36:37]
	global_load_dwordx4 v[20:23], v[36:37], off
	global_load_dwordx4 v[24:27], v[36:37], off offset:512
	s_barrier
	v_add_u32_e32 v52, v133, v170
	v_mov_b32_e32 v44, v156
	v_mov_b32_e32 v45, v135
	v_mov_b32_e32 v40, 0
	s_mov_b32 s0, 16
	v_mov_b32_e32 v41, v40
	v_mov_b32_e32 v42, v40
	v_mov_b32_e32 v43, v40
	s_waitcnt vmcnt(5)
	ds_write_b128 v52, v[4:7]
	s_waitcnt vmcnt(4)
	ds_write_b128 v188, v[8:11]
	s_waitcnt vmcnt(3)
	ds_write_b128 v189, v[12:15]
	s_waitcnt vmcnt(2)
	ds_write_b128 v190, v[16:19]
	s_waitcnt vmcnt(0)
	v_lshl_add_u32 v52, v173, 4, v171
	v_mov_b32_e32 v28, v20
	v_mov_b32_e32 v29, v24
	v_mov_b32_e32 v30, v21
	v_mov_b32_e32 v31, v25
	v_mov_b32_e32 v32, v22
	v_mov_b32_e32 v33, v26
	v_mov_b32_e32 v34, v23
	v_mov_b32_e32 v35, v27
	ds_write_b128 v52, v[28:31]
	ds_write_b128 v52, v[32:35] offset:16
	v_mov_b32_e32 v38, v40
	v_mov_b32_e32 v39, v40
	v_mov_b32_e32 v36, v40
	v_mov_b32_e32 v37, v40
	s_waitcnt lgkmcnt(0)
	s_barrier
	v_readfirstlane_b32 s82, v1
	s_ashr_i32 s83, s8, 1
	s_nop 3
	s_cmp_ge_i32 s82, s83
	s_cbranch_scc1 .Lgate_skip
	v_mov_b32_e32 v202, v45
	v_add_u32_e32 v203, 0x11000, v44
	ds_read_b128 v[4:7], v202
	ds_read_b128 v[8:11], v203
	ds_read_b128 v[12:15], v203 offset:16
	ds_read_b128 v[16:19], v203 offset:32
	ds_read_b128 v[20:23], v203 offset:48
	ds_read_b128 v[24:27], v203 offset:1024
	ds_read_b128 v[28:31], v203 offset:1040
	ds_read_b128 v[32:35], v203 offset:1056
	ds_read_b128 v[88:91], v203 offset:1072
	s_waitcnt lgkmcnt(7)
	ds_read_b128 v[92:95], v203 offset:2048
	ds_read_b128 v[96:99], v203 offset:2064
	ds_read_b128 v[100:103], v203 offset:2080
	ds_read_b128 v[104:107], v203 offset:2096
	ds_read_b128 v[108:111], v203 offset:3072
	ds_read_b128 v[112:115], v203 offset:3088
	ds_read_b128 v[194:197], v203 offset:3104
	ds_read_b128 v[198:201], v203 offset:3120

.Lgate_skip:
	s_ashr_i32 s47, s8, 1
	v_cmp_gt_i32_e32 vcc, s47, v128
	s_nop 1
	v_cndmask_b32_e32 v40, v215, v40, vcc
	v_cmp_gt_i32_e32 vcc, s47, v1
	s_nop 1
	v_cndmask_b32_e32 v41, v215, v41, vcc
	v_cmp_gt_i32_e32 vcc, s47, v121
	ds_write2_b32 v184, v41, v40 offset1:1
	s_nop 0
	v_cndmask_b32_e32 v40, v215, v43, vcc
	v_cmp_gt_i32_e32 vcc, s47, v130
	s_nop 1
	v_cndmask_b32_e32 v41, v215, v42, vcc
	v_cmp_gt_i32_e32 vcc, s47, v129
	ds_write2_b32 v185, v41, v40 offset1:1
	s_nop 0
	v_cndmask_b32_e32 v39, v215, v39, vcc
	v_cmp_gt_i32_e32 vcc, s47, v132
	s_nop 1
	v_cndmask_b32_e32 v38, v215, v38, vcc
	v_cmp_gt_i32_e32 vcc, s47, v131
	ds_write2_b32 v186, v38, v39 offset1:1
	s_nop 0
	v_cndmask_b32_e32 v37, v215, v37, vcc
	v_cmp_gt_i32_e32 vcc, s47, v134
	s_nop 1
	v_cndmask_b32_e32 v36, v215, v36, vcc
	ds_write2_b32 v187, v36, v37 offset1:1
	s_waitcnt lgkmcnt(0)
	s_lshl_b32 s82, s47, 8
	s_ashr_i32 s83, s82, 31
	v_lshl_add_u64 v[4:5], v[140:141], 0, s[82:83]
	v_mov_b64_e32 v[6:7], s[88:89]
	v_lshl_add_u64 v[28:29], s[82:83], 1, v[118:119]
	v_mad_u64_u32 v[6:7], s[82:83], v4, s72, v[6:7]
	v_mad_i32_i24 v7, v5, s72, v7
	v_lshl_add_u64 v[4:5], v[6:7], 0, s[20:21]
	v_lshl_add_u64 v[30:31], v[4:5], 0, v[2:3]
	v_add_co_u32_e32 v4, vcc, s3, v30
	s_mov_b32 s87, 0x3d000
	s_nop 0
	v_addc_co_u32_e32 v5, vcc, 0, v31, vcc
	v_add_co_u32_e32 v12, vcc, s87, v30
	v_lshl_add_u64 v[8:9], v[28:29], 0, v[146:147]
	s_nop 0
	v_addc_co_u32_e32 v13, vcc, 0, v31, vcc
	v_add_co_u32_e32 v20, vcc, 0x79000, v30
	v_lshl_add_u64 v[16:17], v[28:29], 0, v[148:149]
	s_nop 0
	v_addc_co_u32_e32 v21, vcc, 0, v31, vcc
	v_add_co_u32_e32 v30, vcc, 0xb5000, v30
	v_lshl_add_u64 v[24:25], v[28:29], 0, v[150:151]
	s_nop 0
	v_addc_co_u32_e32 v31, vcc, 0, v31, vcc
	v_lshl_add_u64 v[32:33], v[28:29], 0, v[152:153]
	global_load_dwordx4 v[4:7], v[4:5], off offset:1024
	s_nop 0
	global_load_dwordx4 v[8:11], v[8:9], off
	s_nop 0
	global_load_dwordx4 v[12:15], v[12:13], off offset:1024
	s_nop 0
	global_load_dwordx4 v[16:19], v[16:17], off
	s_nop 0
	global_load_dwordx4 v[20:23], v[20:21], off offset:1024
	s_nop 0
	global_load_dwordx4 v[24:27], v[24:25], off
	s_nop 0
	global_load_dwordx4 v[28:31], v[30:31], off offset:1024
	s_nop 0
	global_load_dwordx4 v[32:35], v[32:33], off
	s_barrier
	s_and_saveexec_b64 s[0:1], s[4:5]
	s_cbranch_execz .LBB0_97
	ds_read2_b32 v[36:37], v191 offset1:1
	ds_read2_b32 v[38:39], v191 offset0:2 offset1:3
	ds_read2_b32 v[40:41], v191 offset0:4 offset1:5
	ds_read2_b32 v[42:43], v191 offset0:6 offset1:7
	ds_read2_b32 v[44:45], v191 offset0:8 offset1:9
	ds_read2_b32 v[46:47], v191 offset0:10 offset1:11
	ds_read2_b32 v[48:49], v191 offset0:12 offset1:13
	ds_read2_b32 v[50:51], v191 offset0:14 offset1:15
	ds_read2_b32 v[54:55], v191 offset0:16 offset1:17
	ds_read2_b32 v[56:57], v191 offset0:18 offset1:19
	ds_read2_b32 v[58:59], v191 offset0:20 offset1:21
	ds_read2_b32 v[60:61], v191 offset0:22 offset1:23
	ds_read2_b32 v[62:63], v191 offset0:24 offset1:25
	ds_read2_b32 v[64:65], v191 offset0:26 offset1:27
	ds_read2_b32 v[66:67], v191 offset0:28 offset1:29
	ds_read2_b32 v[68:69], v191 offset0:30 offset1:31
	s_waitcnt lgkmcnt(14)
	v_cmp_nlg_f32_e32 vcc, s73, v36
	s_nop 1
	v_cndmask_b32_e32 v70, v36, v215, vcc
	v_cndmask_b32_e64 v53, 0, -1, vcc
	v_cmp_gt_f32_e32 vcc, v37, v70
	s_nop 1
	v_cndmask_b32_e32 v70, v70, v37, vcc
	v_cndmask_b32_e64 v53, v53, 1, vcc
	v_cmp_gt_f32_e32 vcc, v38, v70
	s_nop 1
	v_cndmask_b32_e32 v70, v70, v38, vcc
	v_cndmask_b32_e64 v53, v53, 2, vcc
	v_cmp_gt_f32_e32 vcc, v39, v70
	s_nop 1
	v_cndmask_b32_e32 v70, v70, v39, vcc
	v_cndmask_b32_e64 v53, v53, 3, vcc
	s_waitcnt lgkmcnt(13)
	v_cmp_gt_f32_e32 vcc, v40, v70
	s_nop 1
	v_cndmask_b32_e32 v70, v70, v40, vcc
	v_cndmask_b32_e64 v53, v53, 4, vcc
	v_cmp_gt_f32_e32 vcc, v41, v70
	s_nop 1
	v_cndmask_b32_e32 v70, v70, v41, vcc
	v_cndmask_b32_e64 v53, v53, 5, vcc
	s_waitcnt lgkmcnt(12)
	v_cmp_gt_f32_e32 vcc, v42, v70
	s_nop 1
	v_cndmask_b32_e32 v70, v70, v42, vcc
	v_cndmask_b32_e64 v53, v53, 6, vcc
	v_cmp_gt_f32_e32 vcc, v43, v70
	s_nop 1
	v_cndmask_b32_e32 v70, v70, v43, vcc
	v_cndmask_b32_e64 v53, v53, 7, vcc
	s_waitcnt lgkmcnt(11)
	v_cmp_gt_f32_e32 vcc, v44, v70
	s_nop 1
	v_cndmask_b32_e32 v70, v70, v44, vcc
	v_cndmask_b32_e64 v53, v53, 8, vcc
	v_cmp_gt_f32_e32 vcc, v45, v70
	s_nop 1
	v_cndmask_b32_e32 v70, v70, v45, vcc
	v_cndmask_b32_e64 v53, v53, 9, vcc
	s_waitcnt lgkmcnt(10)
	v_cmp_gt_f32_e32 vcc, v46, v70
	s_nop 1
	v_cndmask_b32_e32 v70, v70, v46, vcc
	v_cndmask_b32_e64 v53, v53, 10, vcc
	v_cmp_gt_f32_e32 vcc, v47, v70
	s_nop 1
	v_cndmask_b32_e32 v70, v70, v47, vcc
	v_cndmask_b32_e64 v53, v53, 11, vcc
	s_waitcnt lgkmcnt(9)
	v_cmp_gt_f32_e32 vcc, v48, v70
	s_nop 1
	v_cndmask_b32_e32 v70, v70, v48, vcc
	v_cndmask_b32_e64 v53, v53, 12, vcc
	v_cmp_gt_f32_e32 vcc, v49, v70
	s_nop 1
	v_cndmask_b32_e32 v70, v70, v49, vcc
	v_cndmask_b32_e64 v53, v53, 13, vcc
	s_waitcnt lgkmcnt(8)
	v_cmp_gt_f32_e32 vcc, v50, v70
	s_nop 1
	v_cndmask_b32_e32 v70, v70, v50, vcc
	v_cndmask_b32_e64 v53, v53, 14, vcc
	v_cmp_gt_f32_e32 vcc, v51, v70
	s_nop 1
	v_cndmask_b32_e32 v70, v70, v51, vcc
	v_cndmask_b32_e64 v53, v53, 15, vcc
	s_waitcnt lgkmcnt(7)
	v_cmp_gt_f32_e32 vcc, v54, v70
	s_nop 1
	v_cndmask_b32_e32 v70, v70, v54, vcc
	v_cndmask_b32_e64 v53, v53, 16, vcc
	v_cmp_gt_f32_e32 vcc, v55, v70
	s_nop 1
	v_cndmask_b32_e32 v70, v70, v55, vcc
	v_cndmask_b32_e64 v53, v53, 17, vcc
	s_waitcnt lgkmcnt(6)
	v_cmp_gt_f32_e32 vcc, v56, v70
	s_nop 1
	v_cndmask_b32_e32 v70, v70, v56, vcc
	v_cndmask_b32_e64 v53, v53, 18, vcc
	v_cmp_gt_f32_e32 vcc, v57, v70
	s_nop 1
	v_cndmask_b32_e32 v70, v70, v57, vcc
	v_cndmask_b32_e64 v53, v53, 19, vcc
	s_waitcnt lgkmcnt(5)
	v_cmp_gt_f32_e32 vcc, v58, v70
	s_nop 1
	v_cndmask_b32_e32 v70, v70, v58, vcc
	v_cndmask_b32_e64 v53, v53, 20, vcc
	v_cmp_gt_f32_e32 vcc, v59, v70
	s_nop 1
	v_cndmask_b32_e32 v70, v70, v59, vcc
	v_cndmask_b32_e64 v53, v53, 21, vcc
	s_waitcnt lgkmcnt(4)
	v_cmp_gt_f32_e32 vcc, v60, v70
	s_nop 1
	v_cndmask_b32_e32 v70, v70, v60, vcc
	v_cndmask_b32_e64 v53, v53, 22, vcc
	v_cmp_gt_f32_e32 vcc, v61, v70
	s_nop 1
	v_cndmask_b32_e32 v70, v70, v61, vcc
	v_cndmask_b32_e64 v53, v53, 23, vcc
	s_waitcnt lgkmcnt(3)
	v_cmp_gt_f32_e32 vcc, v62, v70
	s_nop 1
	v_cndmask_b32_e32 v70, v70, v62, vcc
	v_cndmask_b32_e64 v53, v53, 24, vcc
	v_cmp_gt_f32_e32 vcc, v63, v70
	s_nop 1
	v_cndmask_b32_e32 v70, v70, v63, vcc
	v_cndmask_b32_e64 v53, v53, 25, vcc
	s_waitcnt lgkmcnt(2)
	v_cmp_gt_f32_e32 vcc, v64, v70
	s_nop 1
	v_cndmask_b32_e32 v70, v70, v64, vcc
	v_cndmask_b32_e64 v53, v53, 26, vcc
	v_cmp_gt_f32_e32 vcc, v65, v70
	s_nop 1
	v_cndmask_b32_e32 v70, v70, v65, vcc
	v_cndmask_b32_e64 v53, v53, 27, vcc
	s_waitcnt lgkmcnt(1)
	v_cmp_gt_f32_e32 vcc, v66, v70
	s_nop 1
	v_cndmask_b32_e32 v70, v70, v66, vcc
	v_cndmask_b32_e64 v53, v53, 28, vcc
	v_cmp_gt_f32_e32 vcc, v67, v70
	s_nop 1
	v_cndmask_b32_e32 v70, v70, v67, vcc
	v_cndmask_b32_e64 v53, v53, 29, vcc
	s_waitcnt lgkmcnt(0)
	v_cmp_gt_f32_e32 vcc, v68, v70
	s_nop 1
	v_cndmask_b32_e32 v70, v70, v68, vcc
	v_cndmask_b32_e64 v53, v53, 30, vcc
	v_cmp_ngt_f32_e32 vcc, v69, v70
	s_nop 1
	v_cndmask_b32_e32 v53, 31, v53, vcc
	v_lshlrev_b32_e64 v70, v53, 1
	v_cmp_lt_i32_e32 vcc, -1, v53
	s_nop 1
	v_cndmask_b32_e32 v70, 0, v70, vcc
	v_cmp_ne_u32_e32 vcc, 0, v53
	s_nop 1
	v_cndmask_b32_e32 v36, v215, v36, vcc
	v_cmp_ne_u32_e32 vcc, 1, v53
	s_nop 1
	v_cndmask_b32_e32 v37, v215, v37, vcc
	v_cmp_ne_u32_e32 vcc, 2, v53
	s_nop 1
	v_cndmask_b32_e32 v38, v215, v38, vcc
	v_cmp_ne_u32_e32 vcc, 3, v53
	s_nop 1
	v_cndmask_b32_e32 v39, v215, v39, vcc
	v_cmp_ne_u32_e32 vcc, 4, v53
	s_nop 1
	v_cndmask_b32_e32 v40, v215, v40, vcc
	v_cmp_ne_u32_e32 vcc, 5, v53
	s_nop 1
	v_cndmask_b32_e32 v41, v215, v41, vcc
	v_cmp_ne_u32_e32 vcc, 6, v53
	s_nop 1
	v_cndmask_b32_e32 v42, v215, v42, vcc
	v_cmp_ne_u32_e32 vcc, 7, v53
	s_nop 1
	v_cndmask_b32_e32 v43, v215, v43, vcc
	v_cmp_ne_u32_e32 vcc, 8, v53
	s_nop 1
	v_cndmask_b32_e32 v44, v215, v44, vcc
	v_cmp_ne_u32_e32 vcc, 9, v53
	s_nop 1
	v_cndmask_b32_e32 v45, v215, v45, vcc
	v_cmp_ne_u32_e32 vcc, 10, v53
	s_nop 1
	v_cndmask_b32_e32 v46, v215, v46, vcc
	v_cmp_ne_u32_e32 vcc, 11, v53
	s_nop 1
	v_cndmask_b32_e32 v47, v215, v47, vcc
	v_cmp_ne_u32_e32 vcc, 12, v53
	s_nop 1
	v_cndmask_b32_e32 v48, v215, v48, vcc
	v_cmp_ne_u32_e32 vcc, 13, v53
	s_nop 1
	v_cndmask_b32_e32 v49, v215, v49, vcc
	v_cmp_ne_u32_e32 vcc, 14, v53
	s_nop 1
	v_cndmask_b32_e32 v50, v215, v50, vcc
	v_cmp_ne_u32_e32 vcc, 15, v53
	s_nop 1
	v_cndmask_b32_e32 v51, v215, v51, vcc
	v_cmp_ne_u32_e32 vcc, 16, v53
	s_nop 1
	v_cndmask_b32_e32 v54, v215, v54, vcc
	v_cmp_ne_u32_e32 vcc, 17, v53
	s_nop 1
	v_cndmask_b32_e32 v55, v215, v55, vcc
	v_cmp_ne_u32_e32 vcc, 18, v53
	s_nop 1
	v_cndmask_b32_e32 v56, v215, v56, vcc
	v_cmp_ne_u32_e32 vcc, 19, v53
	s_nop 1
	v_cndmask_b32_e32 v57, v215, v57, vcc
	v_cmp_ne_u32_e32 vcc, 20, v53
	s_nop 1
	v_cndmask_b32_e32 v58, v215, v58, vcc
	v_cmp_ne_u32_e32 vcc, 21, v53
	s_nop 1
	v_cndmask_b32_e32 v59, v215, v59, vcc
	v_cmp_ne_u32_e32 vcc, 22, v53
	s_nop 1
	v_cndmask_b32_e32 v60, v215, v60, vcc
	v_cmp_ne_u32_e32 vcc, 23, v53
	s_nop 1
	v_cndmask_b32_e32 v61, v215, v61, vcc
	v_cmp_ne_u32_e32 vcc, 24, v53
	s_nop 1
	v_cndmask_b32_e32 v62, v215, v62, vcc
	v_cmp_ne_u32_e32 vcc, 25, v53
	s_nop 1
	v_cndmask_b32_e32 v63, v215, v63, vcc
	v_cmp_ne_u32_e32 vcc, 26, v53
	s_nop 1
	v_cndmask_b32_e32 v64, v215, v64, vcc
	v_cmp_ne_u32_e32 vcc, 27, v53
	s_nop 1
	v_cndmask_b32_e32 v65, v215, v65, vcc
	v_cmp_ne_u32_e32 vcc, 28, v53
	s_nop 1
	v_cndmask_b32_e32 v66, v215, v66, vcc
	v_cmp_ne_u32_e32 vcc, 29, v53
	s_nop 1
	v_cndmask_b32_e32 v67, v215, v67, vcc
	v_cmp_ne_u32_e32 vcc, 30, v53
	s_nop 1
	v_cndmask_b32_e32 v68, v215, v68, vcc
	v_cmp_ne_u32_e32 vcc, 31, v53
	s_nop 1
	v_cndmask_b32_e32 v53, v215, v69, vcc
	v_cmp_nlg_f32_e32 vcc, s73, v36
	v_lshl_or_b32 v69, 1, s47, v70
	s_nop 0
	v_cndmask_b32_e32 v71, v36, v215, vcc
	v_cndmask_b32_e64 v70, 0, -1, vcc
	v_cmp_gt_f32_e32 vcc, v37, v71
	s_nop 1
	v_cndmask_b32_e32 v71, v71, v37, vcc
	v_cndmask_b32_e64 v70, v70, 1, vcc
	v_cmp_gt_f32_e32 vcc, v38, v71
	s_nop 1
	v_cndmask_b32_e32 v71, v71, v38, vcc
	v_cndmask_b32_e64 v70, v70, 2, vcc
	v_cmp_gt_f32_e32 vcc, v39, v71
	s_nop 1
	v_cndmask_b32_e32 v71, v71, v39, vcc
	v_cndmask_b32_e64 v70, v70, 3, vcc
	v_cmp_gt_f32_e32 vcc, v40, v71
	s_nop 1
	v_cndmask_b32_e32 v71, v71, v40, vcc
	v_cndmask_b32_e64 v70, v70, 4, vcc
	v_cmp_gt_f32_e32 vcc, v41, v71
	s_nop 1
	v_cndmask_b32_e32 v71, v71, v41, vcc
	v_cndmask_b32_e64 v70, v70, 5, vcc
	v_cmp_gt_f32_e32 vcc, v42, v71
	s_nop 1
	v_cndmask_b32_e32 v71, v71, v42, vcc
	v_cndmask_b32_e64 v70, v70, 6, vcc
	v_cmp_gt_f32_e32 vcc, v43, v71
	s_nop 1
	v_cndmask_b32_e32 v71, v71, v43, vcc
	v_cndmask_b32_e64 v70, v70, 7, vcc
	v_cmp_gt_f32_e32 vcc, v44, v71
	s_nop 1
	v_cndmask_b32_e32 v71, v71, v44, vcc
	v_cndmask_b32_e64 v70, v70, 8, vcc
	v_cmp_gt_f32_e32 vcc, v45, v71
	s_nop 1
	v_cndmask_b32_e32 v71, v71, v45, vcc
	v_cndmask_b32_e64 v70, v70, 9, vcc
	v_cmp_gt_f32_e32 vcc, v46, v71
	s_nop 1
	v_cndmask_b32_e32 v71, v71, v46, vcc
	v_cndmask_b32_e64 v70, v70, 10, vcc
	v_cmp_gt_f32_e32 vcc, v47, v71
	s_nop 1
	v_cndmask_b32_e32 v71, v71, v47, vcc
	v_cndmask_b32_e64 v70, v70, 11, vcc
	v_cmp_gt_f32_e32 vcc, v48, v71
	s_nop 1
	v_cndmask_b32_e32 v71, v71, v48, vcc
	v_cndmask_b32_e64 v70, v70, 12, vcc
	v_cmp_gt_f32_e32 vcc, v49, v71
	s_nop 1
	v_cndmask_b32_e32 v71, v71, v49, vcc
	v_cndmask_b32_e64 v70, v70, 13, vcc
	v_cmp_gt_f32_e32 vcc, v50, v71
	s_nop 1
	v_cndmask_b32_e32 v71, v71, v50, vcc
	v_cndmask_b32_e64 v70, v70, 14, vcc
	v_cmp_gt_f32_e32 vcc, v51, v71
	s_nop 1
	v_cndmask_b32_e32 v71, v71, v51, vcc
	v_cndmask_b32_e64 v70, v70, 15, vcc
	v_cmp_gt_f32_e32 vcc, v54, v71
	s_nop 1
	v_cndmask_b32_e32 v71, v71, v54, vcc
	v_cndmask_b32_e64 v70, v70, 16, vcc
	v_cmp_gt_f32_e32 vcc, v55, v71
	s_nop 1
	v_cndmask_b32_e32 v71, v71, v55, vcc
	v_cndmask_b32_e64 v70, v70, 17, vcc
	v_cmp_gt_f32_e32 vcc, v56, v71
	s_nop 1
	v_cndmask_b32_e32 v71, v71, v56, vcc
	v_cndmask_b32_e64 v70, v70, 18, vcc
	v_cmp_gt_f32_e32 vcc, v57, v71
	s_nop 1
	v_cndmask_b32_e32 v71, v71, v57, vcc
	v_cndmask_b32_e64 v70, v70, 19, vcc
	v_cmp_gt_f32_e32 vcc, v58, v71
	s_nop 1
	v_cndmask_b32_e32 v71, v71, v58, vcc
	v_cndmask_b32_e64 v70, v70, 20, vcc
	v_cmp_gt_f32_e32 vcc, v59, v71
	s_nop 1
	v_cndmask_b32_e32 v71, v71, v59, vcc
	v_cndmask_b32_e64 v70, v70, 21, vcc
	v_cmp_gt_f32_e32 vcc, v60, v71
	s_nop 1
	v_cndmask_b32_e32 v71, v71, v60, vcc
	v_cndmask_b32_e64 v70, v70, 22, vcc
	v_cmp_gt_f32_e32 vcc, v61, v71
	s_nop 1
	v_cndmask_b32_e32 v71, v71, v61, vcc
	v_cndmask_b32_e64 v70, v70, 23, vcc
	v_cmp_gt_f32_e32 vcc, v62, v71
	s_nop 1
	v_cndmask_b32_e32 v71, v71, v62, vcc
	v_cndmask_b32_e64 v70, v70, 24, vcc
	v_cmp_gt_f32_e32 vcc, v63, v71
	s_nop 1
	v_cndmask_b32_e32 v71, v71, v63, vcc
	v_cndmask_b32_e64 v70, v70, 25, vcc
	v_cmp_gt_f32_e32 vcc, v64, v71
	s_nop 1
	v_cndmask_b32_e32 v71, v71, v64, vcc
	v_cndmask_b32_e64 v70, v70, 26, vcc
	v_cmp_gt_f32_e32 vcc, v65, v71
	s_nop 1
	v_cndmask_b32_e32 v71, v71, v65, vcc
	v_cndmask_b32_e64 v70, v70, 27, vcc
	v_cmp_gt_f32_e32 vcc, v66, v71
	s_nop 1
	v_cndmask_b32_e32 v71, v71, v66, vcc
	v_cndmask_b32_e64 v70, v70, 28, vcc
	v_cmp_gt_f32_e32 vcc, v67, v71
	s_nop 1
	v_cndmask_b32_e32 v71, v71, v67, vcc
	v_cndmask_b32_e64 v70, v70, 29, vcc
	v_cmp_gt_f32_e32 vcc, v68, v71
	s_nop 1
	v_cndmask_b32_e32 v71, v71, v68, vcc
	v_cndmask_b32_e64 v70, v70, 30, vcc
	v_cmp_ngt_f32_e32 vcc, v53, v71
	s_nop 1
	v_cndmask_b32_e32 v70, 31, v70, vcc
	v_lshlrev_b32_e64 v71, v70, 1
	v_cmp_lt_i32_e32 vcc, -1, v70
	s_nop 1
	v_cndmask_b32_e32 v71, 0, v71, vcc
	v_cmp_ne_u32_e32 vcc, 0, v70
	s_nop 1
	v_cndmask_b32_e32 v36, v215, v36, vcc
	v_cmp_ne_u32_e32 vcc, 1, v70
	s_nop 1
	v_cndmask_b32_e32 v37, v215, v37, vcc
	v_cmp_ne_u32_e32 vcc, 2, v70
	s_nop 1
	v_cndmask_b32_e32 v38, v215, v38, vcc
	v_cmp_ne_u32_e32 vcc, 3, v70
	s_nop 1
	v_cndmask_b32_e32 v39, v215, v39, vcc
	v_cmp_ne_u32_e32 vcc, 4, v70
	s_nop 1
	v_cndmask_b32_e32 v40, v215, v40, vcc
	v_cmp_ne_u32_e32 vcc, 5, v70
	s_nop 1
	v_cndmask_b32_e32 v41, v215, v41, vcc
	v_cmp_ne_u32_e32 vcc, 6, v70
	s_nop 1
	v_cndmask_b32_e32 v42, v215, v42, vcc
	v_cmp_ne_u32_e32 vcc, 7, v70
	s_nop 1
	v_cndmask_b32_e32 v43, v215, v43, vcc
	v_cmp_ne_u32_e32 vcc, 8, v70
	s_nop 1
	v_cndmask_b32_e32 v44, v215, v44, vcc
	v_cmp_ne_u32_e32 vcc, 9, v70
	s_nop 1
	v_cndmask_b32_e32 v45, v215, v45, vcc
	v_cmp_ne_u32_e32 vcc, 10, v70
	s_nop 1
	v_cndmask_b32_e32 v46, v215, v46, vcc
	v_cmp_ne_u32_e32 vcc, 11, v70
	s_nop 1
	v_cndmask_b32_e32 v47, v215, v47, vcc
	v_cmp_ne_u32_e32 vcc, 12, v70
	s_nop 1
	v_cndmask_b32_e32 v48, v215, v48, vcc
	v_cmp_ne_u32_e32 vcc, 13, v70
	s_nop 1
	v_cndmask_b32_e32 v49, v215, v49, vcc
	v_cmp_ne_u32_e32 vcc, 14, v70
	s_nop 1
	v_cndmask_b32_e32 v50, v215, v50, vcc
	v_cmp_ne_u32_e32 vcc, 15, v70
	s_nop 1
	v_cndmask_b32_e32 v51, v215, v51, vcc
	v_cmp_ne_u32_e32 vcc, 16, v70
	s_nop 1
	v_cndmask_b32_e32 v54, v215, v54, vcc
	v_cmp_ne_u32_e32 vcc, 17, v70
	s_nop 1
	v_cndmask_b32_e32 v55, v215, v55, vcc
	v_cmp_ne_u32_e32 vcc, 18, v70
	s_nop 1
	v_cndmask_b32_e32 v56, v215, v56, vcc
	v_cmp_ne_u32_e32 vcc, 19, v70
	s_nop 1
	v_cndmask_b32_e32 v57, v215, v57, vcc
	v_cmp_ne_u32_e32 vcc, 20, v70
	s_nop 1
	v_cndmask_b32_e32 v58, v215, v58, vcc
	v_cmp_ne_u32_e32 vcc, 21, v70
	s_nop 1
	v_cndmask_b32_e32 v59, v215, v59, vcc
	v_cmp_ne_u32_e32 vcc, 22, v70
	s_nop 1
	v_cndmask_b32_e32 v60, v215, v60, vcc
	v_cmp_ne_u32_e32 vcc, 23, v70
	s_nop 1
	v_cndmask_b32_e32 v61, v215, v61, vcc
	v_cmp_ne_u32_e32 vcc, 24, v70
	s_nop 1
	v_cndmask_b32_e32 v62, v215, v62, vcc
	v_cmp_ne_u32_e32 vcc, 25, v70
	s_nop 1
	v_cndmask_b32_e32 v63, v215, v63, vcc
	v_cmp_ne_u32_e32 vcc, 26, v70
	s_nop 1
	v_cndmask_b32_e32 v64, v215, v64, vcc
	v_cmp_ne_u32_e32 vcc, 27, v70
	s_nop 1
	v_cndmask_b32_e32 v65, v215, v65, vcc
	v_cmp_ne_u32_e32 vcc, 28, v70
	s_nop 1
	v_cndmask_b32_e32 v66, v215, v66, vcc
	v_cmp_ne_u32_e32 vcc, 29, v70
	s_nop 1
	v_cndmask_b32_e32 v67, v215, v67, vcc
	v_cmp_ne_u32_e32 vcc, 30, v70
	s_nop 1
	v_cndmask_b32_e32 v68, v215, v68, vcc
	v_cmp_ne_u32_e32 vcc, 31, v70
	s_nop 1
	v_cndmask_b32_e32 v53, v215, v53, vcc
	v_cmp_nlg_f32_e32 vcc, s73, v36
	s_nop 1
	v_cndmask_b32_e32 v36, v36, v215, vcc
	v_cndmask_b32_e64 v70, 0, -1, vcc
	v_cmp_gt_f32_e32 vcc, v37, v36
	s_nop 1
	v_cndmask_b32_e32 v36, v36, v37, vcc
	v_cndmask_b32_e64 v70, v70, 1, vcc
	v_cmp_gt_f32_e32 vcc, v38, v36
	s_nop 1
	v_cndmask_b32_e32 v36, v36, v38, vcc
	v_cndmask_b32_e64 v37, v70, 2, vcc
	v_cmp_gt_f32_e32 vcc, v39, v36
	s_nop 1
	v_cndmask_b32_e32 v36, v36, v39, vcc
	v_cndmask_b32_e64 v37, v37, 3, vcc
	v_cmp_gt_f32_e32 vcc, v40, v36
	s_nop 1
	v_cndmask_b32_e32 v36, v36, v40, vcc
	v_cndmask_b32_e64 v37, v37, 4, vcc
	v_cmp_gt_f32_e32 vcc, v41, v36
	s_nop 1
	v_cndmask_b32_e32 v36, v36, v41, vcc
	v_cndmask_b32_e64 v37, v37, 5, vcc
	v_cmp_gt_f32_e32 vcc, v42, v36
	s_nop 1
	v_cndmask_b32_e32 v36, v36, v42, vcc
	v_cndmask_b32_e64 v37, v37, 6, vcc
	v_cmp_gt_f32_e32 vcc, v43, v36
	s_nop 1
	v_cndmask_b32_e32 v36, v36, v43, vcc
	v_cndmask_b32_e64 v37, v37, 7, vcc
	v_cmp_gt_f32_e32 vcc, v44, v36
	s_nop 1
	v_cndmask_b32_e32 v36, v36, v44, vcc
	v_cndmask_b32_e64 v37, v37, 8, vcc
	v_cmp_gt_f32_e32 vcc, v45, v36
	s_nop 1
	v_cndmask_b32_e32 v36, v36, v45, vcc
	v_cndmask_b32_e64 v37, v37, 9, vcc
	v_cmp_gt_f32_e32 vcc, v46, v36
	s_nop 1
	v_cndmask_b32_e32 v36, v36, v46, vcc
	v_cndmask_b32_e64 v37, v37, 10, vcc
	v_cmp_gt_f32_e32 vcc, v47, v36
	s_nop 1
	v_cndmask_b32_e32 v36, v36, v47, vcc
	v_cndmask_b32_e64 v37, v37, 11, vcc
	v_cmp_gt_f32_e32 vcc, v48, v36
	s_nop 1
	v_cndmask_b32_e32 v36, v36, v48, vcc
	v_cndmask_b32_e64 v37, v37, 12, vcc
	v_cmp_gt_f32_e32 vcc, v49, v36
	s_nop 1
	v_cndmask_b32_e32 v36, v36, v49, vcc
	v_cndmask_b32_e64 v37, v37, 13, vcc
	v_cmp_gt_f32_e32 vcc, v50, v36
	s_nop 1
	v_cndmask_b32_e32 v36, v36, v50, vcc
	v_cndmask_b32_e64 v37, v37, 14, vcc
	v_cmp_gt_f32_e32 vcc, v51, v36
	s_nop 1
	v_cndmask_b32_e32 v36, v36, v51, vcc
	v_cndmask_b32_e64 v37, v37, 15, vcc
	v_cmp_gt_f32_e32 vcc, v54, v36
	s_nop 1
	v_cndmask_b32_e32 v36, v36, v54, vcc
	v_cndmask_b32_e64 v37, v37, 16, vcc
	v_cmp_gt_f32_e32 vcc, v55, v36
	s_nop 1
	v_cndmask_b32_e32 v36, v36, v55, vcc
	v_cndmask_b32_e64 v37, v37, 17, vcc
	v_cmp_gt_f32_e32 vcc, v56, v36
	s_nop 1
	v_cndmask_b32_e32 v36, v36, v56, vcc
	v_cndmask_b32_e64 v37, v37, 18, vcc
	v_cmp_gt_f32_e32 vcc, v57, v36
	s_nop 1
	v_cndmask_b32_e32 v36, v36, v57, vcc
	v_cndmask_b32_e64 v37, v37, 19, vcc
	v_cmp_gt_f32_e32 vcc, v58, v36
	s_nop 1
	v_cndmask_b32_e32 v36, v36, v58, vcc
	v_cndmask_b32_e64 v37, v37, 20, vcc
	v_cmp_gt_f32_e32 vcc, v59, v36
	s_nop 1
	v_cndmask_b32_e32 v36, v36, v59, vcc
	v_cndmask_b32_e64 v37, v37, 21, vcc
	v_cmp_gt_f32_e32 vcc, v60, v36
	s_nop 1
	v_cndmask_b32_e32 v36, v36, v60, vcc
	v_cndmask_b32_e64 v37, v37, 22, vcc
	v_cmp_gt_f32_e32 vcc, v61, v36
	s_nop 1
	v_cndmask_b32_e32 v36, v36, v61, vcc
	v_cndmask_b32_e64 v37, v37, 23, vcc
	v_cmp_gt_f32_e32 vcc, v62, v36
	s_nop 1
	v_cndmask_b32_e32 v36, v36, v62, vcc
	v_cndmask_b32_e64 v37, v37, 24, vcc
	v_cmp_gt_f32_e32 vcc, v63, v36
	s_nop 1
	v_cndmask_b32_e32 v36, v36, v63, vcc
	v_cndmask_b32_e64 v37, v37, 25, vcc
	v_cmp_gt_f32_e32 vcc, v64, v36
	s_nop 1
	v_cndmask_b32_e32 v36, v36, v64, vcc
	v_cndmask_b32_e64 v37, v37, 26, vcc
	v_cmp_gt_f32_e32 vcc, v65, v36
	s_nop 1
	v_cndmask_b32_e32 v36, v36, v65, vcc
	v_cndmask_b32_e64 v37, v37, 27, vcc
	v_cmp_gt_f32_e32 vcc, v66, v36
	s_nop 1
	v_cndmask_b32_e32 v36, v36, v66, vcc
	v_cndmask_b32_e64 v37, v37, 28, vcc
	v_cmp_gt_f32_e32 vcc, v67, v36
	s_nop 1
	v_cndmask_b32_e32 v36, v36, v67, vcc
	v_cndmask_b32_e64 v37, v37, 29, vcc
	v_cmp_gt_f32_e32 vcc, v68, v36
	s_nop 1
	v_cndmask_b32_e32 v36, v36, v68, vcc
	v_cndmask_b32_e64 v37, v37, 30, vcc
	v_cmp_ngt_f32_e32 vcc, v53, v36
	s_nop 1
	v_cndmask_b32_e32 v36, 31, v37, vcc
	v_lshlrev_b32_e64 v37, v36, 1
	v_cmp_lt_i32_e32 vcc, -1, v36
	s_nop 1
	v_cndmask_b32_e32 v36, 0, v37, vcc
	v_or3_b32 v36, v69, v71, v36
	ds_write_b32 v166, v36
